# SWA attention epilogue widened the same way (v_permlane32_swap lane pairs, 4 dwordx4 stores per lane instead of 8 dwordx2)
# speedup vs baseline: 1.0035x; 1.0008x over previous
; #define LAS __attribute__((address_space(3)))
; __device__ __forceinline__ void swa_attn_phase(LAS unsigned char* lds, const bf16_t* Q, const bf16_t* Kg, const bf16_t* VT, bf16_t* O, const float* bt2, const float* sinks, int G, int bx, const int tid) {
;     const int lane = tid & 63, wid = __builtin_amdgcn_readfirstlane(tid >> 6), r32 = lane & 31, hi = lane >> 5;
;     LAS unsigned char* ks_ = lds; LAS unsigned char* vs_ = lds + SK_BYTES; LAS float* bs_ = (LAS float*)(lds + SB_OFF);
;     for (int L = bx; L < 512; L += G) {
;         const int hk = L & 3, blk = (L >> 2) & 63, b = L >> 8;
;         const size_t rowbase = (size_t)b * SEQ; const int t0 = blk * 128 - 128;
; #pragma unroll
;         for (int i = 0; i < 4; ++i) { const int p = tid + 512 * i, key = p >> 3, pc = p & 7; u32x4 v = {0u, 0u, 0u, 0u};
;             if (t0 + key >= 0) v = *(const u32x4*)(Kg + (rowbase + t0 + key) * 256 + hk * 64 + pc * 8);
;             *(LAS u32x4*)(ks_ + key * SK_STRIDE + pc * 16) = v; }
; #pragma unroll
;         for (int i = 0; i < 4; ++i) { const int p = tid + 512 * i, dv = p >> 5, pc = p & 31; u32x4 v = {0u, 0u, 0u, 0u};
;             if (t0 + pc * 8 >= 0) v = *(const u32x4*)(VT + ((size_t)((b * 4 + hk) * 64 + dv)) * 8192 + t0 + pc * 8);
;             LAS unsigned char* p_ = vs_ + dv * SV_STRIDE + pc * 16; *(LAS u32x2*)p_ = (u32x2){v.x, v.y}; *(LAS u32x2*)(p_ + 8) = (u32x2){v.z, v.w}; }
;         for (int i = tid; i < 1024; i += 512) bs_[i] = bt2[(hk * 8) * 128 + i];
;         __syncthreads();
;         for (int ci = 0; ci < 4; ++ci) {
;             const int c = wid + 8 * ci, g = c >> 2, qs = c & 3, head = hk * 8 + g;
;             const size_t qrow = rowbase + blk * 128 + 32 * qs + r32;
;             bf16x8 qf[4];
; #pragma unroll
;             for (int d0 = 0; d0 < 4; ++d0) qf[d0] = *(const bf16x8*)(Q + qrow * 2048 + head * 64 + d0 * 16 + hi * 8);
;             const float sink2 = sinks[head] * LOG2E;
;             float mrun = sink2, lrun = (hi == 0) ? 1.0f : 0.0f;
;     ...
;             bf16_t* op = O + qrow * 2048 + head * 64 + 4 * hi;
.LBB0_118:
	s_cmp_eq_u32 s68, 1
	s_mov_b64 s[40:41], -1
	s_movk_i32 s76, 0x1ff
	s_cbranch_scc0 .LBB0_182
	s_cmpk_gt_i32 s84, 0x1ff
	v_readfirstlane_b32 s21, v188
	s_cbranch_scc1 .LBB0_181
	v_and_b32_e32 v2, 31, v188
	v_lshlrev_b32_e32 v0, 4, v188
	v_bfe_u32 v3, v188, 5, 1
	v_and_b32_e32 v180, 0x70, v0
	v_lshlrev_b32_e32 v0, 3, v2
	v_add_u32_e32 v4, 0, v180
	v_lshl_add_u64 v[64:65], s[24:25], 0, v[180:181]
	v_not_b32_e32 v84, v0
	v_lshlrev_b32_e32 v180, 4, v2
	v_lshlrev_b32_e32 v0, 4, v3
	v_mov_b32_e32 v1, v181
	v_and_b32_e32 v6, 64, v220
	v_add_u32_e32 v5, 0, v180
	v_lshl_add_u64 v[66:67], s[72:73], 0, v[180:181]
	v_lshlrev_b32_e32 v180, 3, v3
	v_lshl_add_u64 v[68:69], s[14:15], 0, v[0:1]
	v_cmp_eq_u32_e32 vcc, 0, v3
	v_lshlrev_b32_e32 v1, 2, v3
	v_xor_b32_e32 v3, 32, v220
	v_add_u32_e32 v6, 64, v6
	v_max_i32_e32 v13, 0x200, v188
	s_ashr_i32 s21, s21, 6
	v_cndmask_b32_e64 v86, 0, 1.0, vcc
	v_cmp_lt_i32_e32 vcc, v3, v6
	v_add_u32_e32 v189, 0x200, v188
	v_add_u32_e32 v7, 0x400, v188
	v_add_u32_e32 v9, 0x600, v188
	v_sub_u32_e32 v13, v13, v188
	s_and_b32 s46, s21, 3
	v_cndmask_b32_e32 v3, v220, v3, vcc
	v_ashrrev_i32_e32 v72, 3, v188
	s_movk_i32 s42, 0x90
	v_ashrrev_i32_e32 v74, 3, v189
	v_ashrrev_i32_e32 v76, 3, v7
	v_ashrrev_i32_e32 v78, 3, v9
	v_add_u32_e32 v13, 0x1ff, v13
	v_lshlrev_b32_e32 v94, 2, v188
	v_readlane_b32 s47, v255, 24
	s_load_dwordx2 s[50:51], s[4:5], 0xc8
	v_lshlrev_b32_e32 v87, 2, v3
	v_mul_lo_u32 v3, v72, s42
	v_mul_lo_u32 v6, v74, s42
	v_mul_lo_u32 v8, v76, s42
	v_mul_lo_u32 v10, v78, s42
	v_lshrrev_b32_e32 v14, 9, v13
	v_cmp_lt_u32_e64 s[42:43], s76, v13
	v_add_u32_e32 v95, s47, v94
	s_mul_i32 s47, s46, 0x1200
	v_mul_u32_u24_e32 v13, 0x90, v2
	s_lshl_b32 s35, s46, 5
	v_add3_u32 v96, s47, v13, v0
	v_lshlrev_b32_e32 v13, 2, v2
	s_lshl_b32 s46, s46, 6
	v_ashrrev_i32_e32 v88, 5, v188
	s_movk_i32 s52, 0x208
	v_ashrrev_i32_e32 v89, 5, v189
	v_ashrrev_i32_e32 v90, 5, v7
	v_ashrrev_i32_e32 v91, 5, v9
	v_add_u32_e32 v14, 1, v14
	v_sub_u32_e32 v97, v13, v0
	v_mov_b32_e32 v0, s46
	v_mul_lo_u32 v11, v88, s52
	v_mul_lo_u32 v12, v89, s52
	v_mul_lo_u32 v7, v90, s52
	v_mul_lo_u32 v9, v91, s52
	v_and_b32_e32 v92, 0xfffffe, v14
	v_mad_u32_u24 v0, v2, s52, v0
	s_mov_b32 s46, 0x9000
	v_cmp_gt_i32_e64 s[40:41], s3, v188
	v_or_b32_e32 v85, s35, v2
	v_lshl_add_u64 v[70:71], s[48:49], 0, v[180:181]
	v_lshl_add_u64 v[70:71], v[70:71], 0, v[180:181]
	v_ashrrev_i32_e32 v73, 31, v72
	v_ashrrev_i32_e32 v75, 31, v74
	v_ashrrev_i32_e32 v77, 31, v76
	v_ashrrev_i32_e32 v79, 31, v78
	v_lshl_add_u32 v93, v92, 9, v188
	v_cmp_ne_u32_e64 s[44:45], v14, v92
	v_or_b32_e32 v98, 27, v1
	v_sub_u32_e32 v99, v2, v1
	v_add3_u32 v100, v0, v180, s46
	v_add_u32_e32 v101, v4, v3
	v_add_u32_e32 v102, v4, v6
	v_add_u32_e32 v103, v4, v8
	v_add_u32_e32 v104, v4, v10
	v_add3_u32 v105, v5, v7, s46
	v_add3_u32 v106, v5, v9, s46
	v_add3_u32 v107, v5, v11, s46
	v_add3_u32 v108, v5, v12, s46
	s_mov_b32 s62, s84
	s_mov_b32 s63, s84
	s_branch .LBB0_122

; __device__ __forceinline__ unsigned cvt_pk_bf16(float lo, float hi) { unsigned r; asm volatile("v_cvt_pk_bf16_f32 %0, %1, %2" : "=v"(r) : "v"(lo), "v"(hi)); return r; }
; __device__ __forceinline__ void swa_attn_phase(LAS unsigned char* lds, const bf16_t* Q, const bf16_t* Kg, const bf16_t* VT, bf16_t* O, const float* bt2, const float* sinks, int G, int bx, const int tid) {
;     ...
;             lrun += __shfl_xor(lrun, 32);
;             const float inv = 1.0f / lrun;
;             bf16_t* op = O + qrow * 2048 + head * 64 + 4 * hi;
; #pragma unroll
;             for (int dvb = 0; dvb < 2; ++dvb)
; #pragma unroll
;                 for (int g4 = 0; g4 < 4; ++g4) { u32x2 w; w.x = cvt_pk_bf16(o[dvb][4 * g4] * inv, o[dvb][4 * g4 + 1] * inv); w.y = cvt_pk_bf16(o[dvb][4 * g4 + 2] * inv, o[dvb][4 * g4 + 3] * inv);
;                     *(u32x2*)(op + 32 * dvb + 8 * g4) = w; }
.LBB0_145:
	ds_bpermute_b32 v32, v87, v34
	s_add_i32 s58, s58, 1
	s_cmp_eq_u32 s58, 4
	s_waitcnt lgkmcnt(0)
	v_add_f32_e32 v32, v34, v32
	v_div_scale_f32 v33, s[46:47], v32, v32, 1.0
	v_rcp_f32_e32 v34, v33
	s_nop 0
	v_fma_f32 v35, -v33, v34, 1.0
	v_fmac_f32_e32 v34, v35, v34
	v_div_scale_f32 v35, vcc, 1.0, v32, 1.0
	v_mul_f32_e32 v36, v35, v34
	v_fma_f32 v37, -v33, v36, v35
	v_fmac_f32_e32 v36, v37, v34
	v_fma_f32 v33, -v33, v36, v35
	v_div_fmas_f32 v33, v33, v34, v36
	v_div_fixup_f32 v34, v33, v32, 1.0
	v_lshl_add_u64 v[32:33], s[52:53], 1, v[82:83]
	v_mul_f32_e32 v16, v16, v34
	v_mul_f32_e32 v17, v17, v34
	v_mul_f32_e32 v18, v18, v34
	v_mul_f32_e32 v19, v19, v34
	v_mul_f32_e32 v20, v20, v34
	v_mul_f32_e32 v21, v21, v34
	v_mul_f32_e32 v22, v22, v34
	v_mul_f32_e32 v23, v23, v34
	v_cvt_pk_bf16_f32 v16, v16, v17
	v_cvt_pk_bf16_f32 v17, v18, v19
	v_cvt_pk_bf16_f32 v18, v20, v21
	v_cvt_pk_bf16_f32 v19, v22, v23
	v_mul_f32_e32 v24, v24, v34
	v_mul_f32_e32 v25, v25, v34
	v_mul_f32_e32 v26, v26, v34
	v_mul_f32_e32 v27, v27, v34
	v_mul_f32_e32 v28, v28, v34
	v_mul_f32_e32 v29, v29, v34
	v_mul_f32_e32 v30, v30, v34
	v_mul_f32_e32 v31, v31, v34
	v_cvt_pk_bf16_f32 v24, v24, v25
	v_cvt_pk_bf16_f32 v25, v26, v27
	v_cvt_pk_bf16_f32 v26, v28, v29
	v_cvt_pk_bf16_f32 v27, v30, v31
	v_permlane32_swap_b32_e32 v16, v18
	v_permlane32_swap_b32_e32 v17, v19
	global_store_dwordx4 v[32:33], v[16:19], off
	v_mul_f32_e32 v0, v0, v34
	v_mul_f32_e32 v1, v1, v34
	v_mul_f32_e32 v2, v2, v34
	v_mul_f32_e32 v3, v3, v34
	v_mul_f32_e32 v4, v4, v34
	v_mul_f32_e32 v5, v5, v34
	v_mul_f32_e32 v6, v6, v34
	v_mul_f32_e32 v7, v7, v34
	v_cvt_pk_bf16_f32 v0, v0, v1
	v_cvt_pk_bf16_f32 v1, v2, v3
	v_cvt_pk_bf16_f32 v2, v4, v5
	v_cvt_pk_bf16_f32 v3, v6, v7
	v_permlane32_swap_b32_e32 v24, v26
	v_permlane32_swap_b32_e32 v25, v27
	global_store_dwordx4 v[32:33], v[24:27], off offset:32
	v_mul_f32_e32 v8, v8, v34
	v_mul_f32_e32 v9, v9, v34
	v_mul_f32_e32 v10, v10, v34
	v_mul_f32_e32 v11, v11, v34
	v_mul_f32_e32 v12, v12, v34
	v_mul_f32_e32 v13, v13, v34
	v_mul_f32_e32 v14, v14, v34
	v_mul_f32_e32 v15, v15, v34
	v_cvt_pk_bf16_f32 v8, v8, v9
	v_cvt_pk_bf16_f32 v9, v10, v11
	v_cvt_pk_bf16_f32 v10, v12, v13
	v_cvt_pk_bf16_f32 v11, v14, v15
	v_permlane32_swap_b32_e32 v0, v2
	v_permlane32_swap_b32_e32 v1, v3
	global_store_dwordx4 v[32:33], v[0:3], off offset:64
	s_nop 1
	v_permlane32_swap_b32_e32 v8, v10
	v_permlane32_swap_b32_e32 v9, v11
	global_store_dwordx4 v[32:33], v[8:11], off offset:96
	s_nop 1
	s_cbranch_scc1 .LBB0_121
